# v015 + GEMM phase prologues (9 phases): the three K-tile-1 LDS-DMA stages are issued before the first wait (vmcnt(8) instead of vmcnt(2)), so both prologue K-tiles are in flight together
# speedup vs baseline: 1.0051x; 1.0051x over previous
; #define PG8_STAGE(bufoff, gbase, voff) do { _Pragma("unroll") for (int _i = 0; _i < 2; ++_i) \
;         __builtin_amdgcn_global_load_lds((const unsigned*)((const char*)(gbase) + (voff)[_i]), (PG8_LAS unsigned*)(lds + (bufoff) + ldsw + _i * 8192), 16, 0, PG8_LOAD_AUX); } while (0)
; #define PG8_WAIT_V(n) asm volatile("s_waitcnt vmcnt(" #n ")" ::: "memory")
; #define PG8_BAR __builtin_amdgcn_s_barrier()
; template <class Epi, class Sched, bool ALIGN_EPI = false, bool SP2 = false>
; __device__ __forceinline__ void gemm_phase(PG8_LAS unsigned char* lds, const Gemm g, const Sched& S, const Epi& E) {
;     ...
;         PG8_STAGE(PG8_SB(0, 0), cB, voffB); PG8_STAGE(PG8_SB(0, 1), cB + hstepB, voffB); PG8_STAGE(PG8_SA(0, 0), cA, voffA); PG8_STAGE(PG8_SA(0, 1), cA + hstepA, voffA);
;         if (wr == 1) PG8_BAR;
;         PG8_WAIT_V(2); PG8_BAR;
;         PG8_STAGE(PG8_SB(1, 0), cB + kstep, voffB); PG8_STAGE(PG8_SA(1, 0), cA + kstep, voffA); PG8_STAGE(PG8_SB(1, 1), cB + hstepB + kstep, voffB);
;         PG8_WAIT_V(6); PG8_BAR;
.LBB0_209:
	s_mov_b64 s[10:11], 0x80
	s_and_b32 s14, s3, 3
	s_add_i32 m0, s42, 0x18000
	v_lshl_add_u64 v[6:7], v[6:7], 0, s[10:11]
	s_ashr_i32 s47, s86, 31
	s_lshl_b32 s15, s5, 13
	s_lshl_b32 s16, s14, 12
	global_load_lds_dwordx4 v[6:7], off
	v_lshl_add_u64 v[4:5], v[4:5], 0, s[10:11]
	s_add_i32 m0, s42, 0x1a000
	s_add_i32 s48, s42, 0x8000
	s_add_i32 s49, s42, 0xa000
	global_load_lds_dwordx4 v[4:5], off
	v_lshl_add_u64 v[0:1], v[0:1], 0, s[10:11]
	s_mov_b32 m0, s48
	s_add_u32 s12, s22, 0x10080
	global_load_lds_dwordx4 v[0:1], off
	v_lshl_add_u64 v[0:1], v[2:3], 0, s[10:11]
	s_mov_b32 m0, s49
	s_addc_u32 s13, s23, 0
	global_load_lds_dwordx4 v[0:1], off
	s_add_i32 m0, s42, 0x1c000
	v_lshl_add_u64 v[0:1], s[12:13], 0, v[130:131]
	global_load_lds_dwordx4 v[0:1], off
	v_lshl_add_u64 v[0:1], s[12:13], 0, v[134:135]
	s_add_i32 m0, s42, 0x1e000
	s_sext_i32_i16 s1, s2
	global_load_lds_dwordx4 v[0:1], off
	s_waitcnt vmcnt(8)
	s_barrier
	v_bfe_u32 v0, v154, 4, 2
	v_lshlrev_b32_e32 v2, 3, v0
	v_and_b32_e32 v1, 15, v154
	v_lshlrev_b32_e32 v3, 4, v0
	v_lshlrev_b32_e32 v0, 6, v154
	s_movk_i32 s2, 0x3c0
	v_lshl_or_b32 v147, s14, 6, v2
	v_lshlrev_b32_e32 v2, 8, v154
	v_and_or_b32 v4, v0, s2, v3
	v_cmp_gt_u32_e64 s[2:3], 8, v1
	v_lshl_or_b32 v1, v1, 6, v3
	v_and_b32_e32 v2, 0x38000, v2
	v_lshlrev_b32_e32 v3, 11, v10
	v_or3_b32 v2, v8, v2, v3
	v_lshlrev_b32_e32 v0, 2, v154
	v_add_u32_e32 v138, v2, v9
	v_lshlrev_b32_e32 v2, 4, v11
	v_and_b32_e32 v5, 32, v0
	v_and_b32_e32 v6, 7, v154
	s_waitcnt vmcnt(6)
	s_cmpk_lt_u32 s4, 0x100
	v_and_b32_e32 v2, 0x78000, v2
	v_cndmask_b32_e64 v0, 32, 0, s[2:3]
	v_bitop3_b32 v1, v1, s15, v5 bitop3:0xde
	v_bitop3_b32 v146, s16, v4, v5 bitop3:0xf6
	s_cselect_b64 s[12:13], -1, 0
	v_lshl_or_b32 v148, s5, 6, v6
	v_or3_b32 v2, v8, v2, v3
	s_add_i32 s51, 0, 0x10000
	s_add_i32 s52, 0, 0x14000
	s_mov_b32 s50, s86
	v_or_b32_e32 v149, 16, v148
	v_or_b32_e32 v150, 32, v148
	v_or_b32_e32 v151, 48, v148
	v_add_u32_e32 v152, 0x80, v148
	v_add_u32_e32 v155, 0x90, v148
	v_add_u32_e32 v156, 0xa0, v148
	v_add_u32_e32 v157, 0xb0, v148
	v_mov_b32_e32 v139, v137
	v_add_u32_e32 v140, v2, v9
	v_mov_b32_e32 v141, v137
	v_mov_b64_e32 v[142:143], 0x900
	v_mov_b64_e32 v[144:145], 0x8ff
	v_add_u32_e32 v158, s51, v146
	v_add_u32_e32 v159, s52, v146
	v_add_u32_e32 v160, 0, v1
	s_movk_i32 s53, 0x4800
	v_lshlrev_b32_e32 v136, 1, v0
	s_mov_b32 s54, 0x24000
	s_barrier
	s_branch .LBB0_212

; #define PG8_STAGE(bufoff, gbase, voff) do { _Pragma("unroll") for (int _i = 0; _i < 2; ++_i) \
;         __builtin_amdgcn_global_load_lds((const unsigned*)((const char*)(gbase) + (voff)[_i]), (PG8_LAS unsigned*)(lds + (bufoff) + ldsw + _i * 8192), 16, 0, PG8_LOAD_AUX); } while (0)
; #define PG8_WAIT_V(n) asm volatile("s_waitcnt vmcnt(" #n ")" ::: "memory")
; #define PG8_BAR __builtin_amdgcn_s_barrier()
; template <class Epi, class Sched, bool ALIGN_EPI = false, bool SP2 = false>
; __device__ __forceinline__ void gemm_phase(PG8_LAS unsigned char* lds, const Gemm g, const Sched& S, const Epi& E) {
;     ...
;         PG8_STAGE(PG8_SB(0, 0), cB, voffB); PG8_STAGE(PG8_SB(0, 1), cB + hstepB, voffB); PG8_STAGE(PG8_SA(0, 0), cA, voffA); PG8_STAGE(PG8_SA(0, 1), cA + hstepA, voffA);
;         if (wr == 1) PG8_BAR;
;         PG8_WAIT_V(2); PG8_BAR;
;         PG8_STAGE(PG8_SB(1, 0), cB + kstep, voffB); PG8_STAGE(PG8_SA(1, 0), cA + kstep, voffA); PG8_STAGE(PG8_SB(1, 1), cB + hstepB + kstep, voffB);
;         PG8_WAIT_V(6); PG8_BAR;
.LBB0_363:
	s_mov_b64 s[10:11], 0x80
	s_and_b32 s14, s5, 3
	s_add_i32 m0, s44, 0x18000
	v_lshl_add_u64 v[6:7], v[6:7], 0, s[10:11]
	s_lshl_b32 s15, s4, 6
	s_lshl_b32 s1, s4, 13
	s_lshl_b32 s12, s14, 12
	global_load_lds_dwordx4 v[6:7], off
	v_lshl_add_u64 v[4:5], v[4:5], 0, s[10:11]
	s_add_i32 m0, s44, 0x1a000
	s_add_i32 s49, s44, 0x8000
	s_add_i32 s50, s44, 0xa000
	global_load_lds_dwordx4 v[4:5], off
	v_lshl_add_u64 v[0:1], v[0:1], 0, s[10:11]
	s_mov_b32 m0, s49
	s_add_u32 s4, s22, 0x10080
	global_load_lds_dwordx4 v[0:1], off
	v_lshl_add_u64 v[0:1], v[2:3], 0, s[10:11]
	s_mov_b32 m0, s50
	s_addc_u32 s5, s23, 0
	global_load_lds_dwordx4 v[0:1], off
	s_add_i32 m0, s44, 0x1c000
	v_lshl_add_u64 v[0:1], s[4:5], 0, v[132:133]
	global_load_lds_dwordx4 v[0:1], off
	v_lshl_add_u64 v[0:1], s[4:5], 0, v[128:129]
	s_add_i32 m0, s44, 0x1e000
	v_lshlrev_b32_e32 v4, 2, v154
	global_load_lds_dwordx4 v[0:1], off
	s_waitcnt vmcnt(8)
	s_barrier
	v_bfe_u32 v1, v154, 4, 2
	v_and_b32_e32 v0, 15, v154
	v_lshlrev_b32_e32 v2, 3, v1
	v_lshlrev_b32_e32 v1, 4, v1
	v_lshl_or_b32 v3, v0, 6, v1
	v_and_b32_e32 v4, 32, v4
	v_bitop3_b32 v3, v3, s1, v4 bitop3:0xde
	v_lshlrev_b32_e32 v5, 6, v154
	s_movk_i32 s1, 0x3c0
	v_and_or_b32 v1, v5, s1, v1
	s_cmpk_lt_u32 s3, 0x100
	v_bitop3_b32 v146, s12, v1, v4 bitop3:0xf6
	s_cselect_b64 s[12:13], -1, 0
	v_lshl_or_b32 v147, s14, 6, v2
	v_and_b32_e32 v1, 7, v154
	s_add_i32 s4, s15, 0x80
	s_add_i32 s5, s15, 0x90
	s_add_i32 s14, s15, 0xa0
	s_add_i32 s16, s15, 0xb0
	v_or_b32_e32 v148, s15, v1
	v_or_b32_e32 v152, s4, v1
	v_or_b32_e32 v156, s5, v1
	v_or_b32_e32 v157, s14, v1
	v_or_b32_e32 v158, s16, v1
	v_lshlrev_b32_e32 v1, 8, v154
	v_and_b32_e32 v1, 0x38000, v1
	v_lshlrev_b32_e32 v2, 11, v11
	v_or3_b32 v1, v9, v1, v2
	v_add_u32_e32 v138, v1, v10
	v_lshlrev_b32_e32 v1, 4, v8
	s_sext_i32_i16 s1, s2
	s_waitcnt vmcnt(6)
	v_cmp_gt_u32_e64 s[2:3], 8, v0
	v_and_b32_e32 v1, 0x78000, v1
	v_or3_b32 v1, v9, v1, v2
	v_cndmask_b32_e64 v0, 32, 0, s[2:3]
	s_add_i32 s53, 0, 0x10000
	s_add_i32 s54, 0, 0x14000
	s_ashr_i32 s51, s86, 31
	s_mov_b32 s52, s86
	v_or_b32_e32 v149, 16, v148
	v_or_b32_e32 v150, 32, v148
	v_or_b32_e32 v151, 48, v148
	v_mov_b32_e32 v139, v137
	v_add_u32_e32 v140, v1, v10
	v_mov_b32_e32 v141, v137
	v_mov_b64_e32 v[142:143], 0x900
	v_mov_b64_e32 v[144:145], 0x8ff
	v_add_u32_e32 v159, s53, v146
	v_add_u32_e32 v160, s54, v146
	v_add_u32_e32 v161, 0, v3
	s_movk_i32 s55, 0x4800
	v_lshlrev_b32_e32 v136, 1, v0
	s_mov_b32 s56, 0x24000
	s_barrier
	s_branch .LBB0_366

; #define PG8_STAGE(bufoff, gbase, voff) do { _Pragma("unroll") for (int _i = 0; _i < 2; ++_i) \
;         __builtin_amdgcn_global_load_lds((const unsigned*)((const char*)(gbase) + (voff)[_i]), (PG8_LAS unsigned*)(lds + (bufoff) + ldsw + _i * 8192), 16, 0, PG8_LOAD_AUX); } while (0)
; #define PG8_WAIT_V(n) asm volatile("s_waitcnt vmcnt(" #n ")" ::: "memory")
; #define PG8_BAR __builtin_amdgcn_s_barrier()
; template <class Epi, class Sched, bool ALIGN_EPI = false, bool SP2 = false>
; __device__ __forceinline__ void gemm_phase(PG8_LAS unsigned char* lds, const Gemm g, const Sched& S, const Epi& E) {
;     ...
;         PG8_STAGE(PG8_SB(0, 0), cB, voffB); PG8_STAGE(PG8_SB(0, 1), cB + hstepB, voffB); PG8_STAGE(PG8_SA(0, 0), cA, voffA); PG8_STAGE(PG8_SA(0, 1), cA + hstepA, voffA);
;         if (wr == 1) PG8_BAR;
;         PG8_WAIT_V(2); PG8_BAR;
;         PG8_STAGE(PG8_SB(1, 0), cB + kstep, voffB); PG8_STAGE(PG8_SA(1, 0), cA + kstep, voffA); PG8_STAGE(PG8_SB(1, 1), cB + hstepB + kstep, voffB);
;         PG8_WAIT_V(6); PG8_BAR;
.LBB0_575:
	s_mov_b64 s[14:15], 0x80
	v_readlane_b32 s4, v239, 0
	s_and_b32 s55, s3, 3
	s_add_i32 m0, s35, 0x18000
	v_lshl_add_u64 v[6:7], v[6:7], 0, s[14:15]
	s_ashr_i32 s53, s86, 31
	s_ashr_i32 s54, s4, 31
	s_lshl_b32 s56, s2, 6
	s_lshl_b32 s7, s2, 13
	s_lshl_b32 s16, s55, 12
	global_load_lds_dwordx4 v[6:7], off
	v_lshl_add_u64 v[4:5], v[4:5], 0, s[14:15]
	s_add_i32 m0, s35, 0x1a000
	s_add_i32 s57, s35, 0x8000
	s_add_i32 s58, s35, 0xa000
	global_load_lds_dwordx4 v[4:5], off
	v_lshl_add_u64 v[2:3], v[2:3], 0, s[14:15]
	s_mov_b32 m0, s57
	s_add_u32 s2, s20, 0x10080
	global_load_lds_dwordx4 v[2:3], off
	v_lshl_add_u64 v[0:1], v[0:1], 0, s[14:15]
	s_mov_b32 m0, s58
	s_addc_u32 s3, s21, 0
	global_load_lds_dwordx4 v[0:1], off
	s_add_i32 m0, s35, 0x1c000
	v_lshl_add_u64 v[0:1], s[2:3], 0, v[130:131]
	global_load_lds_dwordx4 v[0:1], off
	v_lshl_add_u64 v[0:1], s[2:3], 0, v[134:135]
	s_add_i32 m0, s35, 0x1e000
	v_lshlrev_b32_e32 v3, 6, v154
	global_load_lds_dwordx4 v[0:1], off
	s_waitcnt vmcnt(8)
	s_barrier
	v_bfe_u32 v0, v154, 4, 2
	v_lshlrev_b32_e32 v1, 3, v0
	v_lshlrev_b32_e32 v2, 4, v0
	s_movk_i32 s2, 0x3c0
	v_lshlrev_b32_e32 v4, 2, v154
	v_and_or_b32 v3, v3, s2, v2
	v_and_b32_e32 v4, 32, v4
	v_lshl_or_b32 v156, s55, 6, v1
	v_lshlrev_b32_e32 v1, 8, v154
	v_bitop3_b32 v152, s16, v3, v4 bitop3:0xf6
	v_and_b32_e32 v1, 0x38000, v1
	v_lshlrev_b32_e32 v3, 11, v10
	v_and_b32_e32 v150, 15, v154
	v_or3_b32 v1, v8, v1, v3
	v_cmp_gt_u32_e64 s[4:5], 8, v150
	v_add_u32_e32 v138, v1, v9
	v_lshlrev_b32_e32 v1, 4, v11
	v_cmp_eq_u32_e64 s[2:3], 0, v0
	v_cndmask_b32_e64 v0, 32, 0, s[4:5]
	v_lshl_or_b32 v2, v150, 6, v2
	s_waitcnt vmcnt(6)
	s_cmpk_lt_u32 s6, 0x100
	v_and_b32_e32 v1, 0x78000, v1
	v_bitop3_b32 v2, v2, s7, v4 bitop3:0xde
	s_cselect_b64 s[16:17], -1, 0
	v_or3_b32 v1, v8, v1, v3
	s_add_i32 s60, 0, 0x10000
	s_add_i32 s61, 0, 0x14000
	v_lshlrev_b32_e32 v136, 1, v0
	v_mbcnt_lo_u32_b32 v0, -1, 0
	v_and_b32_e32 v151, 7, v154
	s_mov_b32 s59, s86
	v_mov_b32_e32 v139, v137
	v_add_u32_e32 v140, v1, v9
	v_mov_b32_e32 v141, v137
	v_mov_b64_e32 v[142:143], 0x200
	v_mov_b64_e32 v[144:145], 0x1ff
	v_add_u32_e32 v157, s60, v152
	v_add_u32_e32 v158, s61, v152
	v_add_u32_e32 v159, 0, v2
	v_mbcnt_hi_u32_b32 v160, -1, v0
	s_mov_b32 s62, 0
	s_barrier
	s_branch .LBB0_578

; #define PG8_STAGE(bufoff, gbase, voff) do { _Pragma("unroll") for (int _i = 0; _i < 2; ++_i) \
;         __builtin_amdgcn_global_load_lds((const unsigned*)((const char*)(gbase) + (voff)[_i]), (PG8_LAS unsigned*)(lds + (bufoff) + ldsw + _i * 8192), 16, 0, PG8_LOAD_AUX); } while (0)
; #define PG8_WAIT_V(n) asm volatile("s_waitcnt vmcnt(" #n ")" ::: "memory")
; #define PG8_BAR __builtin_amdgcn_s_barrier()
; template <class Epi, class Sched, bool ALIGN_EPI = false, bool SP2 = false>
; __device__ __forceinline__ void gemm_phase(PG8_LAS unsigned char* lds, const Gemm g, const Sched& S, const Epi& E) {
;     ...
;         PG8_STAGE(PG8_SB(0, 0), cB, voffB); PG8_STAGE(PG8_SB(0, 1), cB + hstepB, voffB); PG8_STAGE(PG8_SA(0, 0), cA, voffA); PG8_STAGE(PG8_SA(0, 1), cA + hstepA, voffA);
;         if (wr == 1) PG8_BAR;
;         PG8_WAIT_V(2); PG8_BAR;
;         PG8_STAGE(PG8_SB(1, 0), cB + kstep, voffB); PG8_STAGE(PG8_SA(1, 0), cA + kstep, voffA); PG8_STAGE(PG8_SB(1, 1), cB + hstepB + kstep, voffB);
;         PG8_WAIT_V(6); PG8_BAR;
.LBB0_666:
	s_lshl_b32 s1, s8, 5
	s_mov_b64 s[8:9], 0x80
	s_and_b32 s16, s1, 0x60
	s_add_i32 m0, s43, 0x18000
	v_lshl_add_u64 v[6:7], v[6:7], 0, s[8:9]
	s_ashr_i32 s50, s86, 31
	s_lshl_b32 s13, s12, 13
	s_lshl_b32 s17, s16, 7
	global_load_lds_dwordx4 v[6:7], off
	v_lshl_add_u64 v[4:5], v[4:5], 0, s[8:9]
	s_add_i32 m0, s43, 0x1a000
	s_add_i32 s51, s43, 0x8000
	s_add_i32 s52, s43, 0xa000
	global_load_lds_dwordx4 v[4:5], off
	v_lshl_add_u64 v[0:1], v[0:1], 0, s[8:9]
	s_mov_b32 m0, s51
	s_add_u32 s14, s22, 0x40080
	global_load_lds_dwordx4 v[0:1], off
	v_lshl_add_u64 v[0:1], v[2:3], 0, s[8:9]
	s_mov_b32 m0, s52
	s_addc_u32 s15, s23, 0
	global_load_lds_dwordx4 v[0:1], off
	s_add_i32 m0, s43, 0x1c000
	v_lshl_add_u64 v[0:1], s[14:15], 0, v[130:131]
	global_load_lds_dwordx4 v[0:1], off
	v_lshl_add_u64 v[0:1], s[14:15], 0, v[134:135]
	s_add_i32 m0, s43, 0x1e000
	v_bfe_u32 v3, v154, 4, 2
	global_load_lds_dwordx4 v[0:1], off
	s_waitcnt vmcnt(8)
	s_barrier
	s_sext_i32_i8 s1, s2
	v_lshlrev_b32_e32 v0, 4, v3
	v_lshlrev_b32_e32 v1, 6, v154
	s_movk_i32 s2, 0x3c0
	v_and_or_b32 v4, v1, s2, v0
	v_lshlrev_b32_e32 v1, 2, v154
	v_and_b32_e32 v5, 32, v1
	v_mov_b32_e32 v1, v131
	v_and_b32_e32 v2, 15, v154
	v_lshl_add_u64 v[136:137], s[82:83], 0, v[0:1]
	v_lshlrev_b32_e32 v1, 8, v154
	v_lshl_or_b32 v152, s12, 6, v2
	v_lshl_or_b32 v0, v2, 6, v0
	v_and_b32_e32 v1, 0x38000, v1
	v_lshlrev_b32_e32 v2, 11, v10
	v_or3_b32 v1, v8, v1, v2
	v_add_u32_e32 v138, v1, v9
	v_lshlrev_b32_e32 v1, 4, v11
	v_bitop3_b32 v0, v0, s13, v5 bitop3:0xde
	s_waitcnt vmcnt(6)
	s_cmpk_lt_u32 s3, 0x100
	v_and_b32_e32 v1, 0x78000, v1
	v_bitop3_b32 v156, s17, v4, v5 bitop3:0xf6
	s_cselect_b64 s[12:13], -1, 0
	v_or3_b32 v1, v8, v1, v2
	s_add_i32 s54, 0, 0x10000
	s_add_i32 s55, 0, 0x14000
	v_add_u32_e32 v160, 0, v0
	v_mbcnt_lo_u32_b32 v0, -1, 0
	s_mov_b32 s53, s86
	v_lshl_or_b32 v157, v3, 3, s16
	v_mov_b32_e32 v139, v131
	v_add_u32_e32 v140, v1, v9
	v_mov_b32_e32 v141, v131
	v_mov_b64_e32 v[142:143], 0xb00
	v_mov_b64_e32 v[144:145], 0xaff
	v_add_u32_e32 v158, s54, v156
	v_add_u32_e32 v159, s55, v156
	v_mbcnt_hi_u32_b32 v161, -1, v0
	v_mov_b32_e32 v162, 0x358637bd
	s_movk_i32 s56, 0x1600
	s_barrier
	s_branch .LBB0_669

; #define PG8_STAGE(bufoff, gbase, voff) do { _Pragma("unroll") for (int _i = 0; _i < 2; ++_i) \
;         __builtin_amdgcn_global_load_lds((const unsigned*)((const char*)(gbase) + (voff)[_i]), (PG8_LAS unsigned*)(lds + (bufoff) + ldsw + _i * 8192), 16, 0, PG8_LOAD_AUX); } while (0)
; #define PG8_WAIT_V(n) asm volatile("s_waitcnt vmcnt(" #n ")" ::: "memory")
; #define PG8_BAR __builtin_amdgcn_s_barrier()
; template <class Epi, class Sched, bool ALIGN_EPI = false, bool SP2 = false>
; __device__ __forceinline__ void gemm_phase(PG8_LAS unsigned char* lds, const Gemm g, const Sched& S, const Epi& E) {
;     ...
;         PG8_STAGE(PG8_SB(0, 0), cB, voffB); PG8_STAGE(PG8_SB(0, 1), cB + hstepB, voffB); PG8_STAGE(PG8_SA(0, 0), cA, voffA); PG8_STAGE(PG8_SA(0, 1), cA + hstepA, voffA);
;         if (wr == 1) PG8_BAR;
;         PG8_WAIT_V(2); PG8_BAR;
;         PG8_STAGE(PG8_SB(1, 0), cB + kstep, voffB); PG8_STAGE(PG8_SA(1, 0), cA + kstep, voffA); PG8_STAGE(PG8_SB(1, 1), cB + hstepB + kstep, voffB);
;         PG8_WAIT_V(6); PG8_BAR;
.LBB0_743:
	s_mov_b64 s[18:19], 0x80
	s_and_b32 s48, s2, 3
	s_add_i32 m0, s35, 0x18000
	v_lshl_add_u64 v[6:7], v[6:7], 0, s[18:19]
	s_lshl_b32 s49, s3, 6
	s_lshl_b32 s5, s3, 13
	s_lshl_b32 s6, s48, 12
	global_load_lds_dwordx4 v[6:7], off
	v_lshl_add_u64 v[4:5], v[4:5], 0, s[18:19]
	s_add_i32 m0, s35, 0x1a000
	s_add_i32 s50, s35, 0x8000
	s_add_i32 s51, s35, 0xa000
	global_load_lds_dwordx4 v[4:5], off
	v_lshl_add_u64 v[2:3], v[2:3], 0, s[18:19]
	s_mov_b32 m0, s50
	s_add_u32 s2, s20, 0x2c080
	global_load_lds_dwordx4 v[2:3], off
	v_lshl_add_u64 v[0:1], v[0:1], 0, s[18:19]
	s_mov_b32 m0, s51
	s_addc_u32 s3, s21, 0
	global_load_lds_dwordx4 v[0:1], off
	s_add_i32 m0, s35, 0x1c000
	v_lshl_add_u64 v[0:1], s[2:3], 0, v[130:131]
	global_load_lds_dwordx4 v[0:1], off
	v_lshl_add_u64 v[0:1], s[2:3], 0, v[134:135]
	s_add_i32 m0, s35, 0x1e000
	v_and_b32_e32 v150, 15, v154
	global_load_lds_dwordx4 v[0:1], off
	s_waitcnt vmcnt(8)
	s_barrier
	v_bfe_u32 v0, v154, 4, 2
	v_lshlrev_b32_e32 v1, 3, v0
	v_lshlrev_b32_e32 v2, 4, v0
	v_lshlrev_b32_e32 v4, 2, v154
	v_lshl_or_b32 v3, v150, 6, v2
	v_and_b32_e32 v4, 32, v4
	v_lshlrev_b32_e32 v5, 6, v154
	s_movk_i32 s2, 0x3c0
	v_lshl_or_b32 v152, s48, 6, v1
	v_add_u16_e32 v1, v8, v9
	v_bitop3_b32 v3, v3, s5, v4 bitop3:0xde
	v_and_or_b32 v2, v5, s2, v2
	s_waitcnt vmcnt(6)
	s_cmpk_lt_u32 s4, 0x100
	v_cmp_gt_u32_e64 s[4:5], 8, v150
	v_lshrrev_b16_e32 v1, 1, v1
	v_bitop3_b32 v151, s6, v2, v4 bitop3:0xf6
	s_cselect_b64 s[36:37], -1, 0
	v_cmp_eq_u32_e64 s[2:3], 0, v0
	v_cndmask_b32_e64 v0, 32, 0, s[4:5]
	v_readlane_b32 s6, v239, 0
	v_add_lshl_u32 v138, v10, v1, 1
	v_add_lshl_u32 v140, v11, v1, 1
	s_add_i32 s55, 0, 0x10000
	s_add_i32 s56, 0, 0x14000
	v_mbcnt_lo_u32_b32 v1, -1, 0
	v_and_b32_e32 v156, 7, v154
	s_ashr_i32 s52, s86, 31
	s_mov_b32 s53, s86
	s_ashr_i32 s54, s6, 31
	v_mov_b32_e32 v139, v137
	v_mov_b32_e32 v141, v137
	v_mov_b64_e32 v[142:143], 0x200
	v_mov_b64_e32 v[144:145], 0x1ff
	v_add_u32_e32 v157, s55, v151
	v_add_u32_e32 v158, s56, v151
	v_add_u32_e32 v159, 0, v3
	v_mbcnt_hi_u32_b32 v160, -1, v1
	v_lshlrev_b32_e32 v136, 1, v0
	s_mov_b32 s57, 0
	s_barrier
	s_branch .LBB0_746

; #define PG8_STAGE(bufoff, gbase, voff) do { _Pragma("unroll") for (int _i = 0; _i < 2; ++_i) \
;         __builtin_amdgcn_global_load_lds((const unsigned*)((const char*)(gbase) + (voff)[_i]), (PG8_LAS unsigned*)(lds + (bufoff) + ldsw + _i * 8192), 16, 0, PG8_LOAD_AUX); } while (0)
; #define PG8_WAIT_V(n) asm volatile("s_waitcnt vmcnt(" #n ")" ::: "memory")
; #define PG8_BAR __builtin_amdgcn_s_barrier()
; template <class Epi, class Sched, bool ALIGN_EPI = false, bool SP2 = false>
; __device__ __forceinline__ void gemm_phase(PG8_LAS unsigned char* lds, const Gemm g, const Sched& S, const Epi& E) {
;     ...
;         PG8_STAGE(PG8_SB(0, 0), cB, voffB); PG8_STAGE(PG8_SB(0, 1), cB + hstepB, voffB); PG8_STAGE(PG8_SA(0, 0), cA, voffA); PG8_STAGE(PG8_SA(0, 1), cA + hstepA, voffA);
;         if (wr == 1) PG8_BAR;
;         PG8_WAIT_V(2); PG8_BAR;
;         PG8_STAGE(PG8_SB(1, 0), cB + kstep, voffB); PG8_STAGE(PG8_SA(1, 0), cA + kstep, voffA); PG8_STAGE(PG8_SB(1, 1), cB + hstepB + kstep, voffB);
;         PG8_WAIT_V(6); PG8_BAR;
.LBB0_840:
	v_readlane_b32 s5, v239, 0
	s_ashr_i32 s53, s86, 31
	s_ashr_i32 s54, s5, 31
	s_cmp_lg_u64 s[82:83], 0
	s_mov_b64 s[16:17], 0x80
	s_cselect_b64 s[14:15], -1, 0
	s_and_b32 s5, s3, 3
	s_add_i32 m0, s35, 0x18000
	v_lshl_add_u64 v[6:7], v[6:7], 0, s[16:17]
	s_lshl_b32 s55, s2, 6
	s_lshl_b32 s7, s2, 13
	s_lshl_b32 s18, s5, 12
	global_load_lds_dwordx4 v[6:7], off
	v_lshl_add_u64 v[4:5], v[4:5], 0, s[16:17]
	s_add_i32 m0, s35, 0x1a000
	s_add_i32 s56, s35, 0x8000
	s_add_i32 s57, s35, 0xa000
	global_load_lds_dwordx4 v[4:5], off
	v_lshl_add_u64 v[0:1], v[0:1], 0, s[16:17]
	s_mov_b32 m0, s56
	s_add_u32 s2, s20, 0x10080
	global_load_lds_dwordx4 v[0:1], off
	v_lshl_add_u64 v[0:1], v[2:3], 0, s[16:17]
	s_mov_b32 m0, s57
	s_addc_u32 s3, s21, 0
	global_load_lds_dwordx4 v[0:1], off
	s_add_i32 m0, s35, 0x1c000
	v_lshl_add_u64 v[0:1], s[2:3], 0, v[130:131]
	global_load_lds_dwordx4 v[0:1], off
	v_lshl_add_u64 v[0:1], s[2:3], 0, v[134:135]
	s_add_i32 m0, s35, 0x1e000
	s_movk_i32 s2, 0x3c0
	global_load_lds_dwordx4 v[0:1], off
	s_waitcnt vmcnt(8)
	s_barrier
	v_bfe_u32 v0, v154, 4, 2
	v_lshlrev_b32_e32 v1, 3, v0
	v_lshlrev_b32_e32 v136, 4, v0
	v_lshlrev_b32_e32 v0, 6, v154
	v_and_or_b32 v2, v0, s2, v136
	v_lshlrev_b32_e32 v0, 2, v154
	v_and_b32_e32 v3, 32, v0
	v_lshl_or_b32 v158, s5, 6, v1
	v_lshlrev_b32_e32 v1, 8, v154
	v_bitop3_b32 v157, s18, v2, v3 bitop3:0xf6
	v_and_b32_e32 v1, 0x38000, v1
	v_lshlrev_b32_e32 v2, 11, v10
	v_or3_b32 v1, v8, v1, v2
	v_and_b32_e32 v151, 15, v154
	v_add_u32_e32 v140, v1, v9
	v_lshlrev_b32_e32 v1, 4, v11
	v_cmp_gt_u32_e64 s[2:3], 8, v151
	v_lshl_or_b32 v4, v151, 6, v136
	s_waitcnt vmcnt(6)
	s_cmpk_lt_u32 s4, 0x100
	v_and_b32_e32 v1, 0x78000, v1
	v_cndmask_b32_e64 v0, 32, 0, s[2:3]
	v_bitop3_b32 v4, v4, s7, v3 bitop3:0xde
	s_cselect_b64 s[18:19], -1, 0
	v_or3_b32 v1, v8, v1, v2
	s_add_i32 s61, 0, 0x10000
	s_add_i32 s62, 0, 0x14000
	v_and_b32_e32 v156, 7, v154
	s_mov_b32 s33, s86
	v_lshl_add_u64 v[138:139], s[82:83], 0, v[136:137]
	s_or_b32 s58, s55, 16
	s_or_b32 s59, s55, 32
	s_or_b32 s60, s55, 48
	v_mov_b32_e32 v141, v137
	v_add_u32_e32 v142, v1, v9
	v_mov_b32_e32 v143, v137
	v_mov_b64_e32 v[144:145], 0x200
	v_mov_b64_e32 v[146:147], 0x1ff
	v_add_u32_e32 v159, s61, v157
	v_add_u32_e32 v160, s62, v157
	v_add_u32_e32 v161, 0, v4
	v_mov_b32_e32 v162, 0x358637bd
	v_lshlrev_b32_e32 v136, 1, v0
	v_mbcnt_lo_u32_b32 v163, -1, 0
	s_barrier
	s_branch .LBB0_843

; #define PG8_STAGE(bufoff, gbase, voff) do { _Pragma("unroll") for (int _i = 0; _i < 2; ++_i) \
;         __builtin_amdgcn_global_load_lds((const unsigned*)((const char*)(gbase) + (voff)[_i]), (PG8_LAS unsigned*)(lds + (bufoff) + ldsw + _i * 8192), 16, 0, PG8_LOAD_AUX); } while (0)
; #define PG8_WAIT_V(n) asm volatile("s_waitcnt vmcnt(" #n ")" ::: "memory")
; #define PG8_BAR __builtin_amdgcn_s_barrier()
; template <class Epi, class Sched, bool ALIGN_EPI = false, bool SP2 = false>
; __device__ __forceinline__ void gemm_phase(PG8_LAS unsigned char* lds, const Gemm g, const Sched& S, const Epi& E) {
;     ...
;         PG8_STAGE(PG8_SB(0, 0), cB, voffB); PG8_STAGE(PG8_SB(0, 1), cB + hstepB, voffB); PG8_STAGE(PG8_SA(0, 0), cA, voffA); PG8_STAGE(PG8_SA(0, 1), cA + hstepA, voffA);
;         if (wr == 1) PG8_BAR;
;         PG8_WAIT_V(2); PG8_BAR;
;         PG8_STAGE(PG8_SB(1, 0), cB + kstep, voffB); PG8_STAGE(PG8_SA(1, 0), cA + kstep, voffA); PG8_STAGE(PG8_SB(1, 1), cB + hstepB + kstep, voffB);
;         PG8_WAIT_V(6); PG8_BAR;
.LBB0_1010:
	s_mov_b64 s[18:19], 0x80
	s_and_b32 s63, s2, 3
	s_add_i32 m0, s47, 0x18000
	v_lshl_add_u64 v[6:7], v[6:7], 0, s[18:19]
	s_lshl_b32 s64, s3, 6
	s_lshl_b32 s5, s3, 13
	s_lshl_b32 s6, s63, 12
	global_load_lds_dwordx4 v[6:7], off
	v_lshl_add_u64 v[4:5], v[4:5], 0, s[18:19]
	s_add_i32 m0, s47, 0x1a000
	s_add_i32 s65, s47, 0x8000
	s_add_i32 s66, s47, 0xa000
	global_load_lds_dwordx4 v[4:5], off
	v_lshl_add_u64 v[2:3], v[2:3], 0, s[18:19]
	s_mov_b32 m0, s65
	s_add_u32 s2, s0, 0x4080
	global_load_lds_dwordx4 v[2:3], off
	v_lshl_add_u64 v[0:1], v[0:1], 0, s[18:19]
	s_mov_b32 m0, s66
	s_addc_u32 s3, s1, 0
	global_load_lds_dwordx4 v[0:1], off
	s_add_i32 m0, s47, 0x1c000
	v_lshl_add_u64 v[0:1], s[2:3], 0, v[130:131]
	global_load_lds_dwordx4 v[0:1], off
	v_lshl_add_u64 v[0:1], s[2:3], 0, v[134:135]
	s_add_i32 m0, s47, 0x1e000
	v_and_b32_e32 v146, 15, v154
	global_load_lds_dwordx4 v[0:1], off
	s_waitcnt vmcnt(8)
	s_barrier
	v_bfe_u32 v0, v154, 4, 2
	v_lshlrev_b32_e32 v2, 4, v0
	v_lshlrev_b32_e32 v4, 2, v154
	v_lshl_or_b32 v3, v146, 6, v2
	v_and_b32_e32 v4, 32, v4
	v_lshlrev_b32_e32 v5, 6, v154
	s_movk_i32 s2, 0x3c0
	v_lshlrev_b32_e32 v1, 3, v0
	v_bitop3_b32 v3, v3, s5, v4 bitop3:0xde
	v_and_or_b32 v2, v5, s2, v2
	s_waitcnt vmcnt(6)
	s_cmpk_lt_u32 s4, 0x100
	v_cmp_gt_u32_e64 s[4:5], 8, v146
	v_bitop3_b32 v147, s6, v2, v4 bitop3:0xf6
	s_cselect_b64 s[36:37], -1, 0
	v_lshl_or_b32 v148, s63, 6, v1
	v_cmp_eq_u32_e64 s[2:3], 0, v0
	v_cndmask_b32_e64 v0, 32, 0, s[4:5]
	v_readlane_b32 s6, v239, 0
	s_add_i32 s70, 0, 0x10000
	s_add_i32 s71, 0, 0x14000
	v_mbcnt_lo_u32_b32 v1, -1, 0
	v_and_b32_e32 v149, 7, v154
	s_ashr_i32 s67, s86, 31
	s_mov_b32 s68, s86
	s_ashr_i32 s69, s6, 31
	v_mov_b64_e32 v[138:139], 0x200
	v_mov_b64_e32 v[140:141], 0x1ff
	v_add_u32_e32 v150, s70, v147
	v_add_u32_e32 v151, s71, v147
	v_add_u32_e32 v152, 0, v3
	v_mbcnt_hi_u32_b32 v155, -1, v1
	v_lshlrev_b32_e32 v136, 1, v0
	s_mov_b32 s72, 0
	s_barrier
	s_branch .LBB0_1013

; #define PG8_STAGE(bufoff, gbase, voff) do { _Pragma("unroll") for (int _i = 0; _i < 2; ++_i) \
;         __builtin_amdgcn_global_load_lds((const unsigned*)((const char*)(gbase) + (voff)[_i]), (PG8_LAS unsigned*)(lds + (bufoff) + ldsw + _i * 8192), 16, 0, PG8_LOAD_AUX); } while (0)
; #define PG8_WAIT_V(n) asm volatile("s_waitcnt vmcnt(" #n ")" ::: "memory")
; #define PG8_BAR __builtin_amdgcn_s_barrier()
; template <class Epi, class Sched, bool ALIGN_EPI = false, bool SP2 = false>
; __device__ __forceinline__ void gemm_phase(PG8_LAS unsigned char* lds, const Gemm g, const Sched& S, const Epi& E) {
;     ...
;         PG8_STAGE(PG8_SB(0, 0), cB, voffB); PG8_STAGE(PG8_SB(0, 1), cB + hstepB, voffB); PG8_STAGE(PG8_SA(0, 0), cA, voffA); PG8_STAGE(PG8_SA(0, 1), cA + hstepA, voffA);
;         if (wr == 1) PG8_BAR;
;         PG8_WAIT_V(2); PG8_BAR;
;         PG8_STAGE(PG8_SB(1, 0), cB + kstep, voffB); PG8_STAGE(PG8_SA(1, 0), cA + kstep, voffA); PG8_STAGE(PG8_SB(1, 1), cB + hstepB + kstep, voffB);
;         PG8_WAIT_V(6); PG8_BAR;
.LBB0_1105:
	s_lshl_b32 s1, s8, 5
	s_mov_b64 s[8:9], 0x80
	s_and_b32 s16, s1, 0x60
	s_add_i32 m0, s45, 0x18000
	v_lshl_add_u64 v[6:7], v[6:7], 0, s[8:9]
	s_lshl_b32 s13, s12, 13
	s_lshl_b32 s17, s16, 7
	global_load_lds_dwordx4 v[6:7], off
	v_lshl_add_u64 v[4:5], v[4:5], 0, s[8:9]
	s_add_i32 m0, s45, 0x1a000
	s_add_i32 s50, s45, 0x8000
	s_add_i32 s51, s45, 0xa000
	global_load_lds_dwordx4 v[4:5], off
	v_lshl_add_u64 v[0:1], v[0:1], 0, s[8:9]
	s_mov_b32 m0, s50
	s_add_u32 s14, s22, 0x40080
	global_load_lds_dwordx4 v[0:1], off
	v_lshl_add_u64 v[0:1], v[2:3], 0, s[8:9]
	s_mov_b32 m0, s51
	s_addc_u32 s15, s23, 0
	global_load_lds_dwordx4 v[0:1], off
	s_add_i32 m0, s45, 0x1c000
	v_lshl_add_u64 v[0:1], s[14:15], 0, v[132:133]
	global_load_lds_dwordx4 v[0:1], off
	v_lshl_add_u64 v[0:1], s[14:15], 0, v[128:129]
	s_add_i32 m0, s45, 0x1e000
	v_bfe_u32 v2, v154, 4, 2
	global_load_lds_dwordx4 v[0:1], off
	s_waitcnt vmcnt(8)
	s_barrier
	v_and_b32_e32 v1, 15, v154
	v_lshlrev_b32_e32 v0, 4, v2
	v_lshlrev_b32_e32 v3, 2, v154
	v_lshl_or_b32 v152, s12, 6, v1
	v_lshl_or_b32 v1, v1, 6, v0
	v_and_b32_e32 v3, 32, v3
	s_sext_i32_i8 s1, s2
	v_bitop3_b32 v4, v1, s13, v3 bitop3:0xde
	v_lshlrev_b32_e32 v1, 6, v154
	s_movk_i32 s2, 0x3c0
	v_and_or_b32 v1, v1, s2, v0
	v_bitop3_b32 v155, s17, v1, v3 bitop3:0xf6
	v_mov_b32_e32 v1, v133
	v_lshl_add_u64 v[136:137], s[82:83], 0, v[0:1]
	v_lshlrev_b32_e32 v0, 8, v154
	v_and_b32_e32 v0, 0x38000, v0
	v_lshlrev_b32_e32 v1, 11, v11
	v_or3_b32 v0, v9, v0, v1
	v_add_u32_e32 v138, v0, v10
	v_lshlrev_b32_e32 v0, 4, v8
	v_and_b32_e32 v0, 0x78000, v0
	s_waitcnt vmcnt(6)
	s_cmpk_lt_u32 s3, 0x100
	v_or3_b32 v0, v9, v0, v1
	s_cselect_b64 s[12:13], -1, 0
	v_add_u32_e32 v140, v0, v10
	s_add_i32 s54, 0, 0x10000
	s_add_i32 s55, 0, 0x14000
	v_mbcnt_lo_u32_b32 v0, -1, 0
	s_ashr_i32 s52, s86, 31
	s_mov_b32 s53, s86
	v_lshl_or_b32 v156, v2, 3, s16
	v_mov_b32_e32 v139, v133
	v_mov_b32_e32 v141, v133
	v_mov_b64_e32 v[142:143], 0xb00
	v_mov_b64_e32 v[144:145], 0xaff
	v_add_u32_e32 v157, s54, v155
	v_add_u32_e32 v158, s55, v155
	v_add_u32_e32 v159, 0, v4
	v_mbcnt_hi_u32_b32 v160, -1, v0
	v_mov_b32_e32 v161, 0x358637bd
	s_movk_i32 s56, 0x1600
	s_barrier
	s_branch .LBB0_1108

; #define PG8_STAGE(bufoff, gbase, voff) do { _Pragma("unroll") for (int _i = 0; _i < 2; ++_i) \
;         __builtin_amdgcn_global_load_lds((const unsigned*)((const char*)(gbase) + (voff)[_i]), (PG8_LAS unsigned*)(lds + (bufoff) + ldsw + _i * 8192), 16, 0, PG8_LOAD_AUX); } while (0)
; #define PG8_WAIT_V(n) asm volatile("s_waitcnt vmcnt(" #n ")" ::: "memory")
; #define PG8_BAR __builtin_amdgcn_s_barrier()
; template <class Epi, class Sched, bool ALIGN_EPI = false, bool SP2 = false>
; __device__ __forceinline__ void gemm_phase(PG8_LAS unsigned char* lds, const Gemm g, const Sched& S, const Epi& E) {
;     ...
;         PG8_STAGE(PG8_SB(0, 0), cB, voffB); PG8_STAGE(PG8_SB(0, 1), cB + hstepB, voffB); PG8_STAGE(PG8_SA(0, 0), cA, voffA); PG8_STAGE(PG8_SA(0, 1), cA + hstepA, voffA);
;         if (wr == 1) PG8_BAR;
;         PG8_WAIT_V(2); PG8_BAR;
;         PG8_STAGE(PG8_SB(1, 0), cB + kstep, voffB); PG8_STAGE(PG8_SA(1, 0), cA + kstep, voffA); PG8_STAGE(PG8_SB(1, 1), cB + hstepB + kstep, voffB);
;         PG8_WAIT_V(6); PG8_BAR;
.LBB0_1182:
	s_mov_b64 s[18:19], 0x80
	s_and_b32 s48, s2, 3
	s_add_i32 m0, s43, 0x18000
	v_lshl_add_u64 v[6:7], v[6:7], 0, s[18:19]
	s_lshl_b32 s49, s3, 6
	s_lshl_b32 s5, s3, 13
	s_lshl_b32 s6, s48, 12
	global_load_lds_dwordx4 v[6:7], off
	v_lshl_add_u64 v[4:5], v[4:5], 0, s[18:19]
	s_add_i32 m0, s43, 0x1a000
	s_add_i32 s50, s43, 0x8000
	s_add_i32 s51, s43, 0xa000
	global_load_lds_dwordx4 v[4:5], off
	v_lshl_add_u64 v[2:3], v[2:3], 0, s[18:19]
	s_mov_b32 m0, s50
	s_add_u32 s2, s20, 0x2c080
	global_load_lds_dwordx4 v[2:3], off
	v_lshl_add_u64 v[0:1], v[0:1], 0, s[18:19]
	s_mov_b32 m0, s51
	s_addc_u32 s3, s21, 0
	global_load_lds_dwordx4 v[0:1], off
	s_add_i32 m0, s43, 0x1c000
	v_lshl_add_u64 v[0:1], s[2:3], 0, v[130:131]
	global_load_lds_dwordx4 v[0:1], off
	v_lshl_add_u64 v[0:1], s[2:3], 0, v[134:135]
	s_add_i32 m0, s43, 0x1e000
	v_and_b32_e32 v150, 15, v154
	global_load_lds_dwordx4 v[0:1], off
	s_waitcnt vmcnt(8)
	s_barrier
	v_bfe_u32 v0, v154, 4, 2
	v_lshlrev_b32_e32 v1, 3, v0
	v_lshlrev_b32_e32 v2, 4, v0
	v_lshlrev_b32_e32 v4, 2, v154
	v_lshl_or_b32 v3, v150, 6, v2
	v_and_b32_e32 v4, 32, v4
	v_lshlrev_b32_e32 v5, 6, v154
	s_movk_i32 s2, 0x3c0
	v_lshl_or_b32 v152, s48, 6, v1
	v_add_u16_e32 v1, v8, v9
	v_bitop3_b32 v3, v3, s5, v4 bitop3:0xde
	v_and_or_b32 v2, v5, s2, v2
	s_waitcnt vmcnt(6)
	s_cmpk_lt_u32 s4, 0x100
	v_cmp_gt_u32_e64 s[4:5], 8, v150
	v_lshrrev_b16_e32 v1, 1, v1
	v_bitop3_b32 v151, s6, v2, v4 bitop3:0xf6
	s_cselect_b64 s[36:37], -1, 0
	v_cmp_eq_u32_e64 s[2:3], 0, v0
	v_cndmask_b32_e64 v0, 32, 0, s[4:5]
	v_readlane_b32 s6, v239, 0
	v_add_lshl_u32 v138, v10, v1, 1
	v_add_lshl_u32 v140, v11, v1, 1
	s_add_i32 s55, 0, 0x10000
	s_add_i32 s56, 0, 0x14000
	v_mbcnt_lo_u32_b32 v1, -1, 0
	v_and_b32_e32 v154, 7, v154
	s_ashr_i32 s52, s86, 31
	s_mov_b32 s53, s86
	s_ashr_i32 s54, s6, 31
	v_mov_b32_e32 v139, v137
	v_mov_b32_e32 v141, v137
	v_mov_b64_e32 v[142:143], 0x200
	v_mov_b64_e32 v[144:145], 0x1ff
	v_add_u32_e32 v155, s55, v151
	v_add_u32_e32 v156, s56, v151
	v_add_u32_e32 v157, 0, v3
	v_mbcnt_hi_u32_b32 v158, -1, v1
	v_lshlrev_b32_e32 v136, 1, v0
	s_mov_b32 s57, 0
	s_barrier
	s_branch .LBB0_1185
